# static_setprio1_waves0to3_in_nsa_loop
# baseline (speedup 1.0000x reference)
.LBB0_421:
	s_add_i32 s0, 0, 0x22ff0
	v_writelane_b32 v254, s0, 7
	s_waitcnt vmcnt(2)
	v_mov_b32_e32 v91, s0
	s_add_i32 s0, 0, 0x19c00
	v_writelane_b32 v254, s0, 8
	s_add_i32 s0, 0, 0x1bc00
	v_writelane_b32 v254, s0, 9
	v_writelane_b32 v254, s86, 10
	v_cmp_eq_u32_e64 s[8:9], 0, v113
	s_add_i32 s65, 0, 0x11c00
	v_writelane_b32 v254, s87, 11
	v_writelane_b32 v254, s88, 12
	s_mov_b32 s43, 0
	v_mov_b32_e32 v77, 0
	v_writelane_b32 v254, s89, 13
	v_writelane_b32 v254, s90, 14
	s_movk_i32 s10, 0x90
	s_waitcnt vmcnt(1)
	v_mov_b32_e32 v92, 0xf149f2ca
	v_writelane_b32 v254, s91, 15
	v_writelane_b32 v254, s92, 16
	v_mbcnt_hi_u32_b32 v174, -1, v230
	v_mov_b32_e32 v93, 0x80
	v_writelane_b32 v254, s93, 17
	v_writelane_b32 v254, s85, 18
	v_writelane_b32 v254, s94, 19
	v_mov_b32_e32 v94, 0x100
	v_mov_b32_e32 v95, 0x200
	v_writelane_b32 v254, s95, 20
	v_writelane_b32 v254, s71, 21
	v_writelane_b32 v254, s72, 22
	v_writelane_b32 v254, s74, 23
	s_waitcnt vmcnt(0)
	v_mov_b32_e32 v96, 0x400
	v_mov_b32_e32 v97, 0x800
	v_writelane_b32 v254, s75, 24
	v_writelane_b32 v254, s96, 25
	v_writelane_b32 v254, s97, 26
	v_writelane_b32 v254, s66, 27
	v_mov_b32_e32 v98, 0x1000
	v_mov_b32_e32 v99, 0x2000
	v_writelane_b32 v254, s67, 28
	v_writelane_b32 v254, s8, 29
	v_mov_b32_e32 v100, 0x4000
	v_mov_b32_e32 v101, 0x8000
	v_writelane_b32 v254, s9, 30
	v_mov_b32_e32 v102, 0xff800000
	v_writelane_b32 v254, s65, 31
	s_mov_b32 s99, 0
	v_readfirstlane_b32 s100, v210
	s_lshr_b32 s100, s100, 8
	s_cmp_eq_u32 s100, 0
	s_cbranch_scc0 .Lnsa_prio_done
	s_setprio 1
